# attention + scan: packed fp32 ops beside MFMAs split into scalar pairs
# baseline (speedup 1.0000x reference)
.LBB0_92:
	s_or_b64 exec, exec, s[24:25]
	v_add_u32_e32 v93, s43, v78
	ds_read_b128 v[112:115], v93
	ds_read_b128 v[116:119], v110
	ds_read_b128 v[120:123], v110 offset:64
	s_mov_b32 s4, 0x3d800000
	s_waitcnt lgkmcnt(2)
	v_mul_f32_e32 v24, v24, v112
	v_mul_f32_e32 v25, v25, v113
	v_mul_f32_e32 v26, v26, v114
	v_mul_f32_e32 v27, v27, v115
	s_waitcnt vmcnt(11) lgkmcnt(1)
	s_nop 0
	v_mfma_f32_16x16x32_bf16 v[24:27], v[116:119], v[68:71], v[24:27]
	s_waitcnt vmcnt(10) lgkmcnt(0)
	v_mfma_f32_16x16x32_bf16 v[24:27], v[120:123], v[72:75], v[24:27]
	ds_read_b128 v[112:115], v93 offset:64
	ds_read_b128 v[116:119], v110 offset:2304
	ds_read_b128 v[120:123], v110 offset:2368
	s_waitcnt lgkmcnt(2)
	v_mul_f32_e32 v12, v12, v112
	v_mul_f32_e32 v13, v13, v113
	v_mul_f32_e32 v14, v14, v114
	v_mul_f32_e32 v15, v15, v115
	s_waitcnt lgkmcnt(1)
	s_nop 0
	v_mfma_f32_16x16x32_bf16 v[12:15], v[116:119], v[68:71], v[12:15]
	s_waitcnt lgkmcnt(0)
	v_mfma_f32_16x16x32_bf16 v[12:15], v[120:123], v[72:75], v[12:15]
	ds_read_b128 v[112:115], v93 offset:128
	ds_read_b128 v[116:119], v110 offset:4608
	ds_read_b128 v[120:123], v110 offset:4672
	s_waitcnt lgkmcnt(2)
	v_mul_f32_e32 v4, v4, v112
	v_mul_f32_e32 v5, v5, v113
	v_mul_f32_e32 v6, v6, v114
	v_mul_f32_e32 v7, v7, v115
	s_waitcnt lgkmcnt(1)
	s_nop 0
	v_mfma_f32_16x16x32_bf16 v[4:7], v[116:119], v[68:71], v[4:7]
	s_waitcnt lgkmcnt(0)
	v_mfma_f32_16x16x32_bf16 v[4:7], v[120:123], v[72:75], v[4:7]
	ds_read_b128 v[112:115], v93 offset:192
	ds_read_b128 v[116:119], v110 offset:6912
	ds_read_b128 v[120:123], v110 offset:6976
	s_waitcnt lgkmcnt(2)
	v_mul_f32_e32 v0, v0, v112
	v_mul_f32_e32 v1, v1, v113
	v_mul_f32_e32 v2, v2, v114
	v_mul_f32_e32 v3, v3, v115
	v_cvt_pk_bf16_f32 v112, v24, v25
	v_cvt_pk_bf16_f32 v113, v26, v27
	s_waitcnt lgkmcnt(1)
	v_mfma_f32_16x16x32_bf16 v[0:3], v[116:119], v[68:71], v[0:3]
	v_add_u32_e32 v69, 0x9000, v111
	v_cvt_pk_bf16_f32 v114, v12, v13
	v_cvt_pk_bf16_f32 v115, v14, v15
	s_waitcnt lgkmcnt(0)
	v_mfma_f32_16x16x32_bf16 v[0:3], v[120:123], v[72:75], v[0:3]
	ds_read2_b64 v[70:73], v69 offset1:4
	v_cvt_pk_bf16_f32 v116, v4, v5
	v_cvt_pk_bf16_f32 v117, v6, v7
	ds_read2_b64 v[120:123], v69 offset0:8 offset1:12
	s_waitcnt lgkmcnt(1)
	v_mfma_f32_16x16x32_bf16 v[70:73], v[112:115], v[70:73], 0
	s_nop 1
	v_cvt_pk_bf16_f32 v118, v0, v1
	v_cvt_pk_bf16_f32 v119, v2, v3
	v_add_u32_e32 v68, s44, v80
	s_waitcnt lgkmcnt(0)
	v_mfma_f32_16x16x32_bf16 v[70:73], v[116:119], v[120:123], v[70:73]
	s_nop 7
	ds_write_b128 v68, v[70:73]
	v_add_u32_e32 v70, 0xb000, v111
	ds_read2_b64 v[72:75], v70 offset0:32 offset1:36
	ds_read2_b64 v[120:123], v70 offset0:40 offset1:44
	s_waitcnt lgkmcnt(1)
	v_mfma_f32_16x16x32_bf16 v[72:75], v[112:115], v[72:75], 0
	v_add_u32_e32 v71, 0xd000, v111
	s_waitcnt lgkmcnt(0)
	v_mfma_f32_16x16x32_bf16 v[72:75], v[116:119], v[120:123], v[72:75]
	s_nop 7
	ds_write_b128 v68, v[72:75] offset:1024
	ds_read2_b64 v[72:75], v71 offset0:64 offset1:68
	ds_read2_b64 v[120:123], v71 offset0:72 offset1:76
	s_waitcnt lgkmcnt(1)
	v_mfma_f32_16x16x32_bf16 v[72:75], v[112:115], v[72:75], 0
	s_waitcnt lgkmcnt(0)
	v_mfma_f32_16x16x32_bf16 v[72:75], v[116:119], v[120:123], v[72:75]
	s_nop 7
	ds_write_b128 v68, v[72:75] offset:2048
	v_add_u32_e32 v72, 0xf000, v111
	ds_read2_b64 v[120:123], v72 offset0:96 offset1:100
	s_waitcnt lgkmcnt(0)
	v_mfma_f32_16x16x32_bf16 v[112:115], v[112:115], v[120:123], 0
	ds_read2_b64 v[120:123], v72 offset0:104 offset1:108
	v_add_u32_e32 v73, s45, v80
	s_waitcnt lgkmcnt(0)
	v_mfma_f32_16x16x32_bf16 v[112:115], v[116:119], v[120:123], v[112:115]
	s_nop 7
	ds_write_b128 v68, v[112:115] offset:3072
	s_waitcnt lgkmcnt(0)
	s_barrier
	ds_read_b128 v[112:115], v73
	ds_read_b128 v[116:119], v73 offset:8192
	s_waitcnt lgkmcnt(0)
	v_add_f32_e32 v74, v114, v118
	v_add_f32_e32 v75, v115, v119
	v_add_f32_e32 v116, v112, v116
	v_add_f32_e32 v117, v113, v117
	ds_read_b128 v[112:115], v73 offset:16384
	s_waitcnt lgkmcnt(0)
	v_add_f32_e32 v74, v74, v114
	v_add_f32_e32 v75, v75, v115
	v_add_f32_e32 v116, v116, v112
	v_add_f32_e32 v117, v117, v113
	ds_read_b128 v[112:115], v73 offset:24576
	s_waitcnt lgkmcnt(0)
	v_add_f32_e32 v74, v74, v114
	v_add_f32_e32 v75, v75, v115
	v_add_f32_e32 v112, v116, v112
	v_add_f32_e32 v113, v117, v113
	v_pk_mul_f32 v[74:75], v[74:75], s[4:5] op_sel_hi:[1,0]
	v_pk_mul_f32 v[112:113], v[112:113], s[4:5] op_sel_hi:[1,0]
	s_nop 0
	v_cvt_pk_bf16_f32 v112, v112, v113
	v_cvt_pk_bf16_f32 v113, v74, v75
	v_add_u32_e32 v74, s34, v33
	v_ashrrev_i32_e32 v75, 31, v74
	v_lshlrev_b64 v[74:75], 12, v[74:75]
	v_lshl_add_u64 v[74:75], v[34:35], 0, v[74:75]
	global_store_dwordx2 v[74:75], v[112:113], off
	s_waitcnt vmcnt(10)
	ds_write_b128 v79, v[28:31]
	s_waitcnt vmcnt(9)
	ds_write_b128 v81, v[40:43] offset:36864
	s_waitcnt vmcnt(8)
	ds_write_b128 v79, v[44:47] offset:9216
	s_waitcnt vmcnt(7)
	ds_write_b128 v81, v[48:51] offset:45312
	s_waitcnt vmcnt(6)
	ds_write_b128 v79, v[52:55] offset:18432
	s_waitcnt vmcnt(5)
	ds_write_b128 v81, v[56:59] offset:53760
	s_waitcnt vmcnt(4)
	ds_write_b128 v79, v[60:63] offset:27648
	s_waitcnt vmcnt(3)
	ds_write_b128 v81, v[64:67] offset:62208
	s_and_saveexec_b64 s[24:25], s[2:3]
	s_cbranch_execz .LBB0_94
	s_waitcnt vmcnt(1)
	ds_write_b128 v91, v[8:11]

.LBB0_136:
	s_lshr_b32 s2, s30, 1
	s_cmp_lt_u32 s30, 2
	s_cselect_b64 vcc, -1, 0
	s_cmp_eq_u32 s2, 1
	s_cselect_b64 s[0:1], -1, 0
	s_cmp_eq_u32 s2, 2
	s_cselect_b64 s[2:3], -1, 0
	v_mov_b32_e32 v129, v72
	v_cndmask_b32_e64 v72, v127, v126, s[2:3]
	v_cndmask_b32_e64 v72, v72, v125, s[0:1]
	s_and_b32 s0, s28, 32
	v_cndmask_b32_e32 v130, v72, v124, vcc
	v_or_b32_e32 v72, s0, v115
	v_lshlrev_b32_e32 v131, 2, v72
	ds_bpermute_b32 v72, v131, v130
	ds_bpermute_b32 v76, v131, v130 offset:8
	ds_bpermute_b32 v80, v131, v130 offset:16
	ds_bpermute_b32 v84, v131, v130 offset:24
	ds_bpermute_b32 v88, v131, v130 offset:32
	ds_bpermute_b32 v92, v131, v130 offset:40
	ds_bpermute_b32 v96, v131, v130 offset:48
	ds_bpermute_b32 v132, v131, v130 offset:56
	ds_bpermute_b32 v136, v131, v130 offset:64
	ds_bpermute_b32 v140, v131, v130 offset:72
	s_waitcnt lgkmcnt(9)
	v_max_i32_e32 v72, 0, v72
	s_waitcnt lgkmcnt(8)
	v_max_i32_e32 v76, 0, v76
	s_waitcnt lgkmcnt(7)
	v_max_i32_e32 v80, 0, v80
	s_waitcnt lgkmcnt(6)
	v_max_i32_e32 v84, 0, v84
	v_lshlrev_b32_e32 v72, 8, v72
	v_mov_b32_e32 v73, v32
	v_lshlrev_b32_e32 v76, 8, v76
	v_mov_b32_e32 v77, v32
	v_lshlrev_b32_e32 v80, 8, v80
	v_mov_b32_e32 v81, v32
	v_lshlrev_b32_e32 v84, 8, v84
	v_mov_b32_e32 v85, v32
	s_waitcnt lgkmcnt(5)
	v_max_i32_e32 v88, 0, v88
	s_waitcnt lgkmcnt(4)
	v_max_i32_e32 v92, 0, v92
	s_waitcnt lgkmcnt(3)
	v_max_i32_e32 v96, 0, v96
	s_waitcnt lgkmcnt(2)
	v_max_i32_e32 v132, 0, v132
	v_lshl_add_u64 v[72:73], v[72:73], 1, v[108:109]
	v_lshl_add_u64 v[76:77], v[76:77], 1, v[108:109]
	v_lshl_add_u64 v[80:81], v[80:81], 1, v[108:109]
	v_lshl_add_u64 v[84:85], v[84:85], 1, v[108:109]
	v_lshlrev_b32_e32 v88, 8, v88
	v_mov_b32_e32 v89, v32
	v_lshlrev_b32_e32 v92, 8, v92
	v_mov_b32_e32 v93, v32
	v_lshlrev_b32_e32 v96, 8, v96
	v_mov_b32_e32 v97, v32
	v_lshlrev_b32_e32 v132, 8, v132
	v_mov_b32_e32 v133, v32
	s_waitcnt lgkmcnt(1)
	v_max_i32_e32 v136, 0, v136
	s_waitcnt lgkmcnt(0)
	v_max_i32_e32 v140, 0, v140
	global_load_dwordx4 v[72:75], v[72:73], off
	v_lshl_add_u64 v[88:89], v[88:89], 1, v[108:109]
	global_load_dwordx4 v[76:79], v[76:77], off
	v_lshl_add_u64 v[92:93], v[92:93], 1, v[108:109]
	global_load_dwordx4 v[80:83], v[80:81], off
	v_lshl_add_u64 v[96:97], v[96:97], 1, v[108:109]
	global_load_dwordx4 v[84:87], v[84:85], off
	v_lshl_add_u64 v[132:133], v[132:133], 1, v[108:109]
	v_lshlrev_b32_e32 v136, 8, v136
	v_mov_b32_e32 v137, v32
	v_lshlrev_b32_e32 v140, 8, v140
	v_mov_b32_e32 v141, v32
	global_load_dwordx4 v[88:91], v[88:89], off
	v_lshl_add_u64 v[136:137], v[136:137], 1, v[108:109]
	global_load_dwordx4 v[92:95], v[92:93], off
	v_lshl_add_u64 v[140:141], v[140:141], 1, v[108:109]
	global_load_dwordx4 v[96:99], v[96:97], off
	s_add_i32 s30, s30, 1
	global_load_dwordx4 v[132:135], v[132:133], off
	global_load_dwordx4 v[136:139], v[136:137], off
	s_add_i32 s28, s28, 32
	global_load_dwordx4 v[144:147], v[140:141], off
	ds_bpermute_b32 v140, v131, v130 offset:80
	v_mov_b32_e32 v141, v32
	s_cmp_eq_u32 s30, 8
	s_waitcnt lgkmcnt(0)
	v_max_i32_e32 v140, 0, v140
	v_lshlrev_b32_e32 v140, 8, v140
	v_lshl_add_u64 v[140:141], v[140:141], 1, v[108:109]
	global_load_dwordx4 v[148:151], v[140:141], off
	ds_bpermute_b32 v140, v131, v130 offset:88
	v_mov_b32_e32 v141, v32
	s_waitcnt lgkmcnt(0)
	v_max_i32_e32 v140, 0, v140
	v_lshlrev_b32_e32 v140, 8, v140
	v_lshl_add_u64 v[140:141], v[140:141], 1, v[108:109]
	global_load_dwordx4 v[152:155], v[140:141], off
	ds_bpermute_b32 v140, v131, v130 offset:96
	v_mov_b32_e32 v141, v32
	s_waitcnt lgkmcnt(0)
	v_max_i32_e32 v140, 0, v140
	v_lshlrev_b32_e32 v140, 8, v140
	v_lshl_add_u64 v[140:141], v[140:141], 1, v[108:109]
	global_load_dwordx4 v[156:159], v[140:141], off
	ds_bpermute_b32 v140, v131, v130 offset:104
	v_mov_b32_e32 v141, v32
	s_waitcnt lgkmcnt(0)
	v_max_i32_e32 v140, 0, v140
	v_lshlrev_b32_e32 v140, 8, v140
	v_lshl_add_u64 v[140:141], v[140:141], 1, v[108:109]
	global_load_dwordx4 v[160:163], v[140:141], off
	ds_bpermute_b32 v140, v131, v130 offset:112
	ds_bpermute_b32 v131, v131, v130 offset:120
	v_mov_b32_e32 v141, v32
	s_waitcnt lgkmcnt(1)
	v_max_i32_e32 v140, 0, v140
	v_lshlrev_b32_e32 v140, 8, v140
	v_lshl_add_u64 v[140:141], v[140:141], 1, v[108:109]
	s_waitcnt lgkmcnt(0)
	v_max_i32_e32 v131, 0, v131
	global_load_dwordx4 v[172:175], v[140:141], off
	v_lshlrev_b32_e32 v140, 8, v131
	v_mov_b32_e32 v141, v32
	v_lshl_add_u64 v[140:141], v[140:141], 1, v[108:109]
	global_load_dwordx4 v[192:195], v[140:141], off
	s_waitcnt vmcnt(15)
	ds_write_b128 v117, v[72:75]
	s_waitcnt vmcnt(14)
	ds_write_b128 v117, v[76:79] offset:1056
	s_waitcnt vmcnt(13)
	ds_write_b128 v117, v[80:83] offset:2112
	s_waitcnt vmcnt(12)
	ds_write_b128 v117, v[84:87] offset:3168
	s_waitcnt vmcnt(11)
	ds_write_b128 v117, v[88:91] offset:4224
	s_waitcnt vmcnt(10)
	ds_write_b128 v117, v[92:95] offset:5280
	s_waitcnt vmcnt(9)
	ds_write_b128 v117, v[96:99] offset:6336
	s_waitcnt vmcnt(8)
	ds_write_b128 v117, v[132:135] offset:7392
	s_waitcnt vmcnt(7)
	ds_write_b128 v117, v[136:139] offset:8448
	s_waitcnt vmcnt(6)
	ds_write_b128 v117, v[144:147] offset:9504
	s_waitcnt vmcnt(5)
	ds_write_b128 v117, v[148:151] offset:10560
	s_waitcnt vmcnt(4)
	ds_write_b128 v117, v[152:155] offset:11616
	s_waitcnt vmcnt(3)
	ds_write_b128 v117, v[156:159] offset:12672
	s_waitcnt vmcnt(2)
	ds_write_b128 v117, v[160:163] offset:13728
	s_waitcnt vmcnt(1)
	ds_write_b128 v117, v[172:175] offset:14784
	s_waitcnt vmcnt(0)
	ds_write_b128 v117, v[192:195] offset:15840
	v_or_b32_e32 v72, s0, v33
	v_or_b32_e32 v73, v72, v180
	v_lshlrev_b32_e32 v73, 2, v73
	ds_bpermute_b32 v138, v73, v130
	v_or_b32_e32 v73, v72, v110
	v_lshlrev_b32_e32 v73, 2, v73
	ds_bpermute_b32 v139, v73, v130
	v_or_b32_e32 v73, v72, v111
	v_lshlrev_b32_e32 v73, 2, v73
	ds_bpermute_b32 v140, v73, v130
	v_or_b32_e32 v73, v72, v112
	v_lshlrev_b32_e32 v73, 2, v73
	v_or_b32_e32 v72, 16, v72
	ds_bpermute_b32 v141, v73, v130
	v_or_b32_e32 v73, v72, v180
	v_lshlrev_b32_e32 v73, 2, v73
	ds_bpermute_b32 v142, v73, v130
	v_or_b32_e32 v73, v72, v110
	v_lshlrev_b32_e32 v73, 2, v73
	ds_bpermute_b32 v143, v73, v130
	v_or_b32_e32 v73, v72, v111
	v_or_b32_e32 v72, v72, v112
	v_lshlrev_b32_e32 v73, 2, v73
	v_lshlrev_b32_e32 v72, 2, v72
	s_mov_b64 s[0:1], 0
	ds_bpermute_b32 v148, v73, v130
	ds_bpermute_b32 v149, v72, v130
	s_waitcnt lgkmcnt(7)
	v_cmp_lt_i32_e32 vcc, -1, v138
	s_waitcnt lgkmcnt(0)
	ds_read_b128 v[228:231], v118
	ds_read_b128 v[232:235], v118 offset:64
	ds_read_b128 v[236:239], v118 offset:128
	ds_read_b128 v[240:243], v118 offset:192
	s_waitcnt lgkmcnt(3)
	v_mfma_f32_16x16x32_bf16 v[134:137], v[228:231], v[196:199], 0
	ds_read_b128 v[228:231], v118 offset:256
	s_waitcnt lgkmcnt(3)
	v_mfma_f32_16x16x32_bf16 v[134:137], v[232:235], v[200:203], v[134:137]
	ds_read_b128 v[232:235], v118 offset:320
	s_waitcnt lgkmcnt(3)
	v_mfma_f32_16x16x32_bf16 v[134:137], v[236:239], v[204:207], v[134:137]
	ds_read_b128 v[236:239], v118 offset:384
	s_waitcnt lgkmcnt(3)
	v_mfma_f32_16x16x32_bf16 v[134:137], v[240:243], v[208:211], v[134:137]
	ds_read_b128 v[240:243], v118 offset:448
	s_waitcnt lgkmcnt(3)
	v_mfma_f32_16x16x32_bf16 v[134:137], v[228:231], v[212:215], v[134:137]
	ds_read_b128 v[228:231], v118 offset:8448
	s_waitcnt lgkmcnt(3)
	v_mfma_f32_16x16x32_bf16 v[134:137], v[232:235], v[216:219], v[134:137]
	ds_read_b128 v[232:235], v118 offset:8512
	s_waitcnt lgkmcnt(3)
	v_mfma_f32_16x16x32_bf16 v[134:137], v[236:239], v[220:223], v[134:137]
	ds_read_b128 v[236:239], v118 offset:8576
	s_waitcnt lgkmcnt(3)
	v_mfma_f32_16x16x32_bf16 v[134:137], v[240:243], v[224:227], v[134:137]
	ds_read_b128 v[240:243], v118 offset:8640
	s_waitcnt lgkmcnt(3)
	v_mfma_f32_16x16x32_bf16 v[72:75], v[228:231], v[196:199], 0
	ds_read_b128 v[228:231], v118 offset:8704
	s_waitcnt lgkmcnt(3)
	v_mfma_f32_16x16x32_bf16 v[72:75], v[232:235], v[200:203], v[72:75]
	ds_read_b128 v[232:235], v118 offset:8768
	s_waitcnt lgkmcnt(3)
	v_mfma_f32_16x16x32_bf16 v[72:75], v[236:239], v[204:207], v[72:75]
	ds_read_b128 v[236:239], v118 offset:8832
	s_waitcnt lgkmcnt(3)
	v_mfma_f32_16x16x32_bf16 v[72:75], v[240:243], v[208:211], v[72:75]
	ds_read_b128 v[240:243], v118 offset:8896
	v_subrev_u32_e32 v80, s29, v142
	v_med3_i32 v80, v80, s4, v189
	v_lshl_add_u32 v80, v80, 6, v116
	ds_read_b32 v80, v80 offset:8192
	s_waitcnt lgkmcnt(4)
	v_mfma_f32_16x16x32_bf16 v[72:75], v[228:231], v[212:215], v[72:75]
	s_waitcnt lgkmcnt(3)
	v_mfma_f32_16x16x32_bf16 v[72:75], v[232:235], v[216:219], v[72:75]
	s_waitcnt lgkmcnt(2)
	v_mfma_f32_16x16x32_bf16 v[72:75], v[236:239], v[220:223], v[72:75]
	s_waitcnt lgkmcnt(1)
	v_mfma_f32_16x16x32_bf16 v[72:75], v[240:243], v[224:227], v[72:75]
	v_subrev_u32_e32 v76, s29, v138
	v_med3_i32 v76, v76, s4, v189
	v_subrev_u32_e32 v77, s29, v139
	v_lshl_add_u32 v76, v76, 6, v116
	v_med3_i32 v77, v77, s4, v189
	v_subrev_u32_e32 v78, s29, v140
	ds_read_b32 v76, v76 offset:8192
	v_lshl_add_u32 v77, v77, 6, v116
	v_med3_i32 v78, v78, s4, v189
	v_subrev_u32_e32 v79, s29, v141
	ds_read_b32 v77, v77 offset:8192
	v_lshl_add_u32 v78, v78, 6, v116
	v_med3_i32 v79, v79, s4, v189
	ds_read_b32 v78, v78 offset:8192
	v_lshl_add_u32 v79, v79, 6, v116
	ds_read_b32 v79, v79 offset:8192
	s_waitcnt lgkmcnt(3)
	v_fmac_f32_e32 v76, 0x3d800000, v134
	v_cndmask_b32_e32 v76, v190, v76, vcc
	s_waitcnt lgkmcnt(2)
	v_fmac_f32_e32 v77, 0x3d800000, v135
	v_cmp_lt_i32_e32 vcc, -1, v139
	s_waitcnt lgkmcnt(1)
	v_fmac_f32_e32 v78, 0x3d800000, v136
	s_waitcnt lgkmcnt(0)
	v_fmac_f32_e32 v79, 0x3d800000, v137
	v_cndmask_b32_e32 v77, v190, v77, vcc
	v_cmp_lt_i32_e32 vcc, -1, v140
	v_fmac_f32_e32 v80, 0x3d800000, v72
	s_nop 0
	v_cndmask_b32_e32 v78, v190, v78, vcc
	v_cmp_lt_i32_e32 vcc, -1, v141
	s_nop 1
	v_cndmask_b32_e32 v79, v190, v79, vcc
	v_cmp_lt_i32_e32 vcc, -1, v142
	v_max_f32_e32 v81, v78, v79
	s_nop 0
	v_cndmask_b32_e32 v72, v190, v80, vcc
	v_subrev_u32_e32 v80, s29, v143
	v_med3_i32 v80, v80, s4, v189
	v_lshl_add_u32 v80, v80, 6, v116
	ds_read_b32 v80, v80 offset:8192
	v_cmp_lt_i32_e32 vcc, -1, v143
	s_waitcnt lgkmcnt(0)
	v_fmac_f32_e32 v80, 0x3d800000, v73
	v_subrev_u32_e32 v73, s29, v148
	v_med3_i32 v73, v73, s4, v189
	v_lshl_add_u32 v73, v73, 6, v116
	ds_read_b32 v73, v73 offset:8192
	v_cndmask_b32_e32 v80, v190, v80, vcc
	v_cmp_lt_i32_e32 vcc, -1, v148
	s_waitcnt lgkmcnt(0)
	v_fmac_f32_e32 v73, 0x3d800000, v74
	v_cndmask_b32_e32 v74, v190, v73, vcc
	v_subrev_u32_e32 v73, s29, v149
	v_med3_i32 v73, v73, s4, v189
	v_lshl_add_u32 v73, v73, 6, v116
	ds_read_b32 v73, v73 offset:8192
	v_cmp_lt_i32_e32 vcc, -1, v149
	s_waitcnt lgkmcnt(0)
	v_fmac_f32_e32 v73, 0x3d800000, v75
	v_cndmask_b32_e32 v75, v190, v73, vcc
	v_max_f32_e32 v82, v74, v75
	v_max_f32_e32 v73, v76, v77
	v_max3_f32 v82, v72, v80, v82
	v_max3_f32 v73, v73, v81, v82
	ds_bpermute_b32 v81, v113, v73
	s_waitcnt lgkmcnt(0)
	v_max_f32_e32 v81, v81, v81
	v_max_f32_e32 v73, v73, v81
	ds_bpermute_b32 v81, v114, v73
	s_waitcnt lgkmcnt(0)
	v_max3_f32 v73, v128, v73, v81
	v_sub_f32_e32 v72, v72, v73
	v_mul_f32_e32 v72, 0x3fb8aa3b, v72
	v_sub_f32_e32 v76, v76, v73
	v_exp_f32_e32 v82, v72
	v_sub_f32_e32 v72, v80, v73
	v_mul_f32_e32 v76, 0x3fb8aa3b, v76
	v_sub_f32_e32 v77, v77, v73
	v_mul_f32_e32 v72, 0x3fb8aa3b, v72
	v_exp_f32_e32 v76, v76
	v_mul_f32_e32 v77, 0x3fb8aa3b, v77
	v_sub_f32_e32 v78, v78, v73
	v_exp_f32_e32 v80, v72
	v_sub_f32_e32 v72, v74, v73
	v_exp_f32_e32 v77, v77
	v_mul_f32_e32 v78, 0x3fb8aa3b, v78
	v_sub_f32_e32 v79, v79, v73
	v_mul_f32_e32 v72, 0x3fb8aa3b, v72
	v_exp_f32_e32 v78, v78
	v_mul_f32_e32 v79, 0x3fb8aa3b, v79
	v_exp_f32_e32 v83, v72
	v_sub_f32_e32 v72, v75, v73
	v_exp_f32_e32 v79, v79
	v_mul_f32_e32 v72, 0x3fb8aa3b, v72
	v_exp_f32_e32 v84, v72
	v_add_f32_e32 v72, 0, v76
	v_add_f32_e32 v72, v77, v72
	v_add_f32_e32 v72, v78, v72
	v_sub_f32_e32 v81, v128, v73
	v_add_f32_e32 v72, v79, v72
	v_mul_f32_e32 v81, 0x3fb8aa3b, v81
	v_add_f32_e32 v72, v82, v72
	v_exp_f32_e32 v86, v81
	v_add_f32_e32 v72, v80, v72
	v_add_f32_e32 v72, v83, v72
	v_cvt_pk_bf16_f32 v74, v76, v77
	v_cvt_pk_bf16_f32 v75, v78, v79
	v_cvt_pk_bf16_f32 v76, v82, v80
	v_cvt_pk_bf16_f32 v77, v83, v84
	ds_read_b64_tr_b16 v[80:81], v119 offset:8448
	ds_read_b64_tr_b16 v[78:79], v119
	ds_read_b64_tr_b16 v[82:83], v119 offset:32
	v_mul_f32_e32 v70, v86, v70
	v_mul_f32_e32 v71, v86, v71
	v_mul_f32_e32 v68, v86, v68
	v_mul_f32_e32 v69, v86, v69
	v_add_f32_e32 v72, v84, v72
	ds_read_b64_tr_b16 v[84:85], v119 offset:8480
	s_waitcnt lgkmcnt(2)
	v_mfma_f32_16x16x32_bf16 v[68:71], v[78:81], v[74:77], v[68:71]
	ds_read_b64_tr_b16 v[78:79], v119 offset:64
	ds_read_b64_tr_b16 v[80:81], v119 offset:8512
	v_mul_f32_e32 v66, v86, v66
	v_mul_f32_e32 v67, v86, v67
	v_mul_f32_e32 v64, v86, v64
	v_mul_f32_e32 v65, v86, v65
	v_mul_f32_e32 v62, v86, v62
	v_mul_f32_e32 v63, v86, v63
	v_mul_f32_e32 v60, v86, v60
	v_mul_f32_e32 v61, v86, v61
	s_waitcnt lgkmcnt(0)
	v_mfma_f32_16x16x32_bf16 v[64:67], v[78:81], v[74:77], v[64:67]
	ds_read_b64_tr_b16 v[78:79], v119 offset:96
	ds_read_b64_tr_b16 v[80:81], v119 offset:8544
	v_mul_f32_e32 v26, v86, v26
	v_mul_f32_e32 v27, v86, v27
	v_mul_f32_e32 v24, v86, v24
	v_mul_f32_e32 v25, v86, v25
	s_waitcnt lgkmcnt(0)
	v_mfma_f32_16x16x32_bf16 v[60:63], v[78:81], v[74:77], v[60:63]
	v_mul_f32_e64 v58, v58, v86
	v_mul_f32_e64 v59, v59, v86
	v_mul_f32_e32 v56, v86, v56
	v_mul_f32_e32 v57, v86, v57
	v_mul_f32_e32 v50, v86, v50
	v_mul_f32_e32 v51, v86, v51
	v_mfma_f32_16x16x32_bf16 v[24:27], v[82:85], v[74:77], v[24:27]
	ds_read_b64_tr_b16 v[80:81], v119 offset:8576
	ds_read_b64_tr_b16 v[78:79], v119 offset:128
	ds_read_b64_tr_b16 v[82:83], v119 offset:160
	ds_read_b64_tr_b16 v[84:85], v119 offset:8608
	v_mul_f32_e32 v48, v86, v48
	v_mul_f32_e32 v49, v86, v49
	s_waitcnt lgkmcnt(2)
	v_mfma_f32_16x16x32_bf16 v[56:59], v[78:81], v[74:77], v[56:59]
	ds_read_b64_tr_b16 v[78:79], v119 offset:192
	ds_read_b64_tr_b16 v[80:81], v119 offset:8640
	v_mul_f32_e32 v54, v86, v54
	v_mul_f32_e32 v55, v86, v55
	v_mul_f32_e32 v52, v86, v52
	v_mul_f32_e32 v53, v86, v53
	s_waitcnt lgkmcnt(0)
	v_mfma_f32_16x16x32_bf16 v[48:51], v[78:81], v[74:77], v[48:51]
	ds_read_b64_tr_b16 v[78:79], v119 offset:224
	ds_read_b64_tr_b16 v[80:81], v119 offset:8672
	v_mul_f32_e32 v46, v86, v46
	v_mul_f32_e32 v47, v86, v47
	v_mul_f32_e32 v44, v86, v44
	v_mul_f32_e32 v45, v86, v45
	v_mfma_f32_16x16x32_bf16 v[52:55], v[82:85], v[74:77], v[52:55]
	v_mul_f32_e64 v42, v42, v86
	v_mul_f32_e64 v43, v43, v86
	v_mul_f32_e32 v40, v86, v40
	v_mul_f32_e32 v41, v86, v41
	v_mul_f32_e32 v22, v86, v22
	v_mul_f32_e32 v23, v86, v23
	s_waitcnt lgkmcnt(0)
	v_mfma_f32_16x16x32_bf16 v[44:47], v[78:81], v[74:77], v[44:47]
	ds_read_b64_tr_b16 v[80:81], v119 offset:8704
	ds_read_b64_tr_b16 v[78:79], v119 offset:256
	ds_read_b64_tr_b16 v[82:83], v119 offset:288
	ds_read_b64_tr_b16 v[84:85], v119 offset:8736
	v_mul_f32_e32 v20, v86, v20
	v_mul_f32_e32 v21, v86, v21
	s_waitcnt lgkmcnt(2)
	v_mfma_f32_16x16x32_bf16 v[40:43], v[78:81], v[74:77], v[40:43]
	ds_read_b64_tr_b16 v[78:79], v119 offset:320
	ds_read_b64_tr_b16 v[80:81], v119 offset:8768
	v_mul_f32_e32 v30, v86, v30
	v_mul_f32_e32 v31, v86, v31
	v_mul_f32_e32 v28, v86, v28
	v_mul_f32_e32 v29, v86, v29
	s_waitcnt lgkmcnt(0)
	v_mfma_f32_16x16x32_bf16 v[20:23], v[78:81], v[74:77], v[20:23]
	ds_read_b64_tr_b16 v[78:79], v119 offset:352
	ds_read_b64_tr_b16 v[80:81], v119 offset:8800
	v_mul_f32_e32 v18, v86, v18
	v_mul_f32_e32 v19, v86, v19
	v_mul_f32_e32 v16, v86, v16
	v_mul_f32_e32 v17, v86, v17
	v_mfma_f32_16x16x32_bf16 v[28:31], v[82:85], v[74:77], v[28:31]
	v_mul_f32_e64 v14, v14, v86
	v_mul_f32_e64 v15, v15, v86
	v_mul_f32_e32 v12, v86, v12
	v_mul_f32_e32 v13, v86, v13
	v_mul_f32_e32 v6, v86, v6
	v_mul_f32_e32 v7, v86, v7
	s_waitcnt lgkmcnt(0)
	v_mfma_f32_16x16x32_bf16 v[16:19], v[78:81], v[74:77], v[16:19]
	ds_read_b64_tr_b16 v[80:81], v119 offset:8832
	ds_read_b64_tr_b16 v[78:79], v119 offset:384
	ds_read_b64_tr_b16 v[82:83], v119 offset:416
	ds_read_b64_tr_b16 v[84:85], v119 offset:8864
	v_mul_f32_e32 v4, v86, v4
	v_mul_f32_e32 v5, v86, v5
	s_waitcnt lgkmcnt(2)
	v_mfma_f32_16x16x32_bf16 v[12:15], v[78:81], v[74:77], v[12:15]
	ds_read_b64_tr_b16 v[78:79], v119 offset:448
	ds_read_b64_tr_b16 v[80:81], v119 offset:8896
	v_mul_f32_e32 v10, v86, v10
	v_mul_f32_e32 v11, v86, v11
	v_mul_f32_e32 v8, v86, v8
	v_mul_f32_e32 v9, v86, v9
	s_waitcnt lgkmcnt(0)
	v_mfma_f32_16x16x32_bf16 v[4:7], v[78:81], v[74:77], v[4:7]
	ds_read_b64_tr_b16 v[78:79], v119 offset:480
	ds_read_b64_tr_b16 v[80:81], v119 offset:8928
	v_mul_f32_e32 v2, v86, v2
	v_mul_f32_e32 v3, v86, v3
	v_mul_f32_e32 v0, v86, v0
	v_mul_f32_e32 v1, v86, v1
	v_mfma_f32_16x16x32_bf16 v[8:11], v[82:85], v[74:77], v[8:11]
	s_waitcnt lgkmcnt(0)
	v_fmac_f32_e32 v72, v129, v86
	s_waitcnt lgkmcnt(0)
	v_mfma_f32_16x16x32_bf16 v[0:3], v[78:81], v[74:77], v[0:3]
	v_mov_b32_e32 v128, v73
	s_cbranch_scc0 .LBB0_136
	ds_bpermute_b32 v73, v113, v72
	v_mov_b32_e32 v124, v123
	v_mov_b32_e32 v125, v122
	v_mov_b32_e32 v126, v121
	v_mov_b32_e32 v127, v120
	s_waitcnt lgkmcnt(0)
	v_add_f32_e32 v72, v72, v73
	ds_bpermute_b32 v73, v114, v72
	s_mov_b32 s2, s25
	s_waitcnt lgkmcnt(0)
	v_add_f32_e32 v72, v72, v73
	v_div_scale_f32 v73, s[0:1], v72, v72, 1.0
	v_rcp_f32_e32 v74, v73
	s_lshl_b64 s[0:1], s[76:77], 13
	s_mov_b32 s76, s38
	v_fma_f32 v75, -v73, v74, 1.0
	v_fmac_f32_e32 v74, v75, v74
	v_div_scale_f32 v75, vcc, 1.0, v72, 1.0
	v_mul_f32_e32 v76, v75, v74
	v_fma_f32 v77, -v73, v76, v75
	v_fmac_f32_e32 v76, v77, v74
	v_fma_f32 v73, -v73, v76, v75
	v_div_fmas_f32 v73, v73, v74, v76
	v_div_fixup_f32 v72, v73, v72, 1.0
	v_mul_f32_e32 v24, v72, v24
	v_mul_f32_e32 v25, v72, v25
	v_mul_f32_e32 v26, v72, v26
	v_mul_f32_e32 v27, v72, v27
	v_lshl_add_u64 v[74:75], v[104:105], 0, s[0:1]
	v_cvt_pk_bf16_f32 v24, v24, v25
	v_cvt_pk_bf16_f32 v25, v26, v27
	global_store_dwordx2 v[74:75], v[24:25], off offset:32
	v_mul_f32_e32 v24, v72, v64
	v_mul_f32_e32 v25, v72, v65
	v_mul_f32_e32 v26, v72, v66
	v_mul_f32_e32 v27, v72, v67
	v_cvt_pk_bf16_f32 v24, v24, v25
	v_cvt_pk_bf16_f32 v25, v26, v27
	global_store_dwordx2 v[74:75], v[24:25], off offset:64
	v_mul_f32_e32 v24, v72, v60
	v_mul_f32_e32 v25, v72, v61
	v_mul_f32_e32 v26, v72, v62
	v_mul_f32_e32 v27, v72, v63
	v_cvt_pk_bf16_f32 v24, v24, v25
	v_cvt_pk_bf16_f32 v25, v26, v27
	global_store_dwordx2 v[74:75], v[24:25], off offset:96
	v_mul_f32_e32 v24, v72, v56
	v_mul_f32_e32 v25, v72, v57
	v_mul_f32_e32 v26, v72, v58
	v_mul_f32_e32 v27, v72, v59
	v_cvt_pk_bf16_f32 v24, v24, v25
	v_cvt_pk_bf16_f32 v25, v26, v27
	global_store_dwordx2 v[74:75], v[24:25], off offset:128
	v_mul_f32_e32 v24, v72, v52
	v_mul_f32_e32 v25, v72, v53
	v_mul_f32_e32 v26, v72, v54
	v_mul_f32_e32 v27, v72, v55
	v_cvt_pk_bf16_f32 v24, v24, v25
	v_cvt_pk_bf16_f32 v25, v26, v27
	global_store_dwordx2 v[74:75], v[24:25], off offset:160
	v_mul_f32_e32 v24, v72, v48
	v_mul_f32_e32 v25, v72, v49
	v_mul_f32_e32 v26, v72, v50
	v_mul_f32_e32 v27, v72, v51
	v_cvt_pk_bf16_f32 v24, v24, v25
	v_cvt_pk_bf16_f32 v25, v26, v27
	global_store_dwordx2 v[74:75], v[24:25], off offset:192
	v_mul_f32_e32 v24, v72, v44
	v_mul_f32_e32 v25, v72, v45
	v_mul_f32_e32 v26, v72, v46
	v_mul_f32_e32 v27, v72, v47
	v_cvt_pk_bf16_f32 v24, v24, v25
	v_cvt_pk_bf16_f32 v25, v26, v27
	global_store_dwordx2 v[74:75], v[24:25], off offset:224
	v_mul_f32_e32 v24, v72, v40
	v_mul_f32_e32 v25, v72, v41
	v_mul_f32_e32 v26, v72, v42
	v_mul_f32_e32 v27, v72, v43
	v_cvt_pk_bf16_f32 v24, v24, v25
	v_cvt_pk_bf16_f32 v25, v26, v27
	v_mul_f32_e32 v68, v72, v68
	v_mul_f32_e32 v69, v72, v69
	v_mul_f32_e32 v70, v72, v70
	v_mul_f32_e32 v71, v72, v71
	global_store_dwordx2 v[74:75], v[24:25], off offset:256
	v_mul_f32_e32 v24, v72, v28
	v_mul_f32_e32 v25, v72, v29
	v_mul_f32_e32 v26, v72, v30
	v_mul_f32_e32 v27, v72, v31
	v_mul_f32_e32 v20, v72, v20
	v_mul_f32_e32 v21, v72, v21
	v_mul_f32_e32 v22, v72, v22
	v_mul_f32_e32 v23, v72, v23
	v_mul_f32_e32 v16, v72, v16
	v_mul_f32_e32 v17, v72, v17
	v_mul_f32_e32 v18, v72, v18
	v_mul_f32_e32 v19, v72, v19
	v_mul_f32_e32 v12, v72, v12
	v_mul_f32_e32 v13, v72, v13
	v_mul_f32_e32 v14, v72, v14
	v_mul_f32_e32 v15, v72, v15
	v_mul_f32_e32 v8, v72, v8
	v_mul_f32_e32 v9, v72, v9
	v_mul_f32_e32 v10, v72, v10
	v_mul_f32_e32 v11, v72, v11
	v_mul_f32_e32 v4, v72, v4
	v_mul_f32_e32 v5, v72, v5
	v_mul_f32_e32 v6, v72, v6
	v_mul_f32_e32 v7, v72, v7
	v_mul_f32_e32 v0, v72, v0
	v_mul_f32_e32 v1, v72, v1
	v_mul_f32_e32 v2, v72, v2
	v_mul_f32_e32 v3, v72, v3
	v_cvt_pk_bf16_f32 v68, v68, v69
	v_cvt_pk_bf16_f32 v69, v70, v71
	v_cvt_pk_bf16_f32 v24, v24, v25
	v_cvt_pk_bf16_f32 v25, v26, v27
	v_cvt_pk_bf16_f32 v20, v20, v21
	v_cvt_pk_bf16_f32 v21, v22, v23
	v_cvt_pk_bf16_f32 v16, v16, v17
	v_cvt_pk_bf16_f32 v17, v18, v19
	v_cvt_pk_bf16_f32 v12, v12, v13
	v_cvt_pk_bf16_f32 v13, v14, v15
	v_cvt_pk_bf16_f32 v8, v8, v9
	v_cvt_pk_bf16_f32 v9, v10, v11
	v_cvt_pk_bf16_f32 v4, v4, v5
	v_cvt_pk_bf16_f32 v5, v6, v7
	v_cvt_pk_bf16_f32 v0, v0, v1
	v_cvt_pk_bf16_f32 v1, v2, v3
	s_and_b64 vcc, exec, s[40:41]
	global_store_dwordx2 v[74:75], v[68:69], off
	global_store_dwordx2 v[74:75], v[24:25], off offset:288
	global_store_dwordx2 v[74:75], v[20:21], off offset:320
	global_store_dwordx2 v[74:75], v[16:17], off offset:352
	global_store_dwordx2 v[74:75], v[12:13], off offset:384
	global_store_dwordx2 v[74:75], v[8:9], off offset:416
	global_store_dwordx2 v[74:75], v[4:5], off offset:448
	global_store_dwordx2 v[74:75], v[0:1], off offset:480
	s_cbranch_vccz .LBB0_128
